# v15_lazy
# speedup vs baseline: 1.0151x; 1.0151x over previous
; #define MFMA32(a, b, c) __builtin_amdgcn_mfma_f32_32x32x16_bf16((a), (b), (c), 0, 0, 0)
; DI f32x16 zero16() { f32x16 z; for (int i = 0; i < 16; ++i) z[i] = 0.f; return z; }
; template <int DQK, int MODE>
; DI void attn_core(const u16* __restrict__ Qg, int ldq, const u16* __restrict__ Kg, int ldk, const u16* __restrict__ Vtg,
;                   const u64* __restrict__ maskg, int q0, float scale, char* smem, int* sflags, f32x16 (&o)[4], float& l_run) {
;     ...
;   for (int it = 0; it < ntiles; ++it, tau += step) {
;     __syncthreads();
;     if (MODE == 2 && it > 0) {
;       if (!(sflags[0] | sflags[1] | sflags[2] | sflags[3] | sflags[4] | sflags[5] | sflags[6] | sflags[7])) break;
;     }
;     if (MODE == 2) gload(tau);
; #pragma unroll
;     for (int i = 0; i < NVK; ++i) {
;       const int v = tid + NT * i, row = v / VPR, c = v % VPR;
;       *(u32x4*)(Ks + row * KSTR + c * 8) = rk[i];
;     }
; #pragma unroll
;     for (int i = 0; i < 2; ++i) {
;       const int v = tid + NT * i, row = v >> 3, c = v & 7;
;       *(u32x4*)(Vs + row * 72 + c * 8) = rv[i];
;     }
;     __syncthreads();
;     if (MODE != 2 && it + 1 < ntiles) gload(tau + step);
;     if (tau * 64 > q0 + 32 * wid + 31) {
;       if (MODE == 2 && lane == 0) sflags[wid] = 1;
;       continue;
;     }
;     u64 mbits = 0;
;     if (MODE == 1) mbits = maskg[(long)qrow * 64 + tau] >> (8 * hh);
;     f32x16 s[2];
;     s[0] = zero16(); s[1] = zero16();
; #pragma unroll
;     for (int kt = 0; kt < 2; ++kt)
; #pragma unroll
;       for (int ks = 0; ks < NKS; ++ks) {
;         const bf16x8 kf = *(const bf16x8*)(Ks + (32 * kt + krow) * KSTR + ks * 16 + hh * 8);
;         s[kt] = MFMA32(kf, qf[ks], s[kt]);
;       }
;     const int kbase = tau * 64 + 8 * hh;
;     if (MODE == 0 || MODE == 1) {
;       const bool need_mask = (MODE == 1) || (tau * 64 + 63 > q0 + 32 * wid);
;       float mx = -1e30f;
;       if (need_mask) {
; #pragma unroll
;         for (int kt = 0; kt < 2; ++kt)
; #pragma unroll
;           for (int i = 0; i < 16; ++i) {
;             bool valid;
;             if (MODE == 1) valid = (mbits >> (32 * kt + 16 * (i >> 3) + (i & 7))) & 1ull;
;             else valid = (kbase + 32 * kt + 16 * (i >> 3) + (i & 7)) <= qrow;
;             s[kt][i] = valid ? s[kt][i] : -1e30f;
;           }
.LBB0_156:
	v_add_u32_e32 v0, s0, v176
	v_mad_i64_i32 v[2:3], s[4:5], v0, s75, v[168:169]
	v_add_u32_e32 v0, s0, v177
	v_mad_i64_i32 v[4:5], s[4:5], v0, s75, v[170:171]
	s_ashr_i32 s1, s0, 31
	s_lshl_b64 s[4:5], s[0:1], 1
	s_nop 0
	s_waitcnt vmcnt(0)
	ds_write_b128 v180, v[156:159]
	ds_write_b128 v181, v[152:155]
	ds_write_b128 v182, v[148:151] offset:17408
	ds_write_b128 v183, v[144:147] offset:17408
	s_waitcnt lgkmcnt(0)
	global_load_dwordx4 v[156:159], v[2:3], off
	global_load_dwordx4 v[152:155], v[4:5], off
	v_lshl_add_u64 v[2:3], v[162:163], 0, s[4:5]
	v_lshl_add_u64 v[4:5], v[166:167], 0, s[4:5]
	global_load_dwordx4 v[148:151], v[2:3], off
	global_load_dwordx4 v[144:147], v[4:5], off
	s_sub_i32 s1, s0, 64
	s_barrier
	v_cmp_le_i32_e32 vcc, s1, v179
	s_and_saveexec_b64 s[4:5], vcc
	s_cbranch_execz .LBB0_155
	v_add_u32_e32 v0, v174, v178
	global_load_dwordx2 v[10:11], v[172:173], off
	ds_read_b128 v[12:15], v0
	ds_read_b128 v[202:205], v0 offset:32
	ds_read_b128 v[210:213], v0 offset:64
	ds_read_b128 v[214:217], v0 offset:96
	ds_read_b128 v[218:221], v0 offset:128
	ds_read_b128 v[226:229], v0 offset:160
	s_waitcnt lgkmcnt(5)
	v_mfma_f32_32x32x16_bf16 v[96:111], v[12:15], v[140:143], 0
	ds_read_b128 v[12:15], v0 offset:192
	s_waitcnt lgkmcnt(5)
	v_mfma_f32_32x32x16_bf16 v[96:111], v[202:205], v[136:139], v[96:111]
	ds_read_b128 v[202:205], v0 offset:224
	s_waitcnt vmcnt(0)
	v_lshrrev_b64 v[8:9], v160, v[10:11]
	s_waitcnt lgkmcnt(5)
	v_mfma_f32_32x32x16_bf16 v[96:111], v[210:213], v[132:135], v[96:111]
	ds_read_b128 v[210:213], v0 offset:8704
	s_waitcnt lgkmcnt(5)
	v_mfma_f32_32x32x16_bf16 v[96:111], v[214:217], v[128:131], v[96:111]
	ds_read_b128 v[214:217], v0 offset:8736
	s_waitcnt lgkmcnt(5)
	v_mfma_f32_32x32x16_bf16 v[96:111], v[218:221], v[124:127], v[96:111]
	ds_read_b128 v[218:221], v0 offset:8768
	s_waitcnt lgkmcnt(5)
	v_mfma_f32_32x32x16_bf16 v[96:111], v[226:229], v[120:123], v[96:111]
	ds_read_b128 v[226:229], v0 offset:8800
	s_waitcnt lgkmcnt(5)
	v_mfma_f32_32x32x16_bf16 v[96:111], v[12:15], v[116:119], v[96:111]
	ds_read_b128 v[12:15], v0 offset:8832
	s_waitcnt lgkmcnt(5)
	v_mfma_f32_32x32x16_bf16 v[96:111], v[202:205], v[112:115], v[96:111]
	ds_read_b128 v[202:205], v0 offset:8864
	s_waitcnt lgkmcnt(5)
	v_mfma_f32_32x32x16_bf16 v[80:95], v[210:213], v[140:143], 0
	ds_read_b128 v[210:213], v0 offset:8896
	s_waitcnt lgkmcnt(5)
	v_mfma_f32_32x32x16_bf16 v[80:95], v[214:217], v[136:139], v[80:95]
	ds_read_b128 v[214:217], v0 offset:8928
	s_waitcnt lgkmcnt(5)
	v_mfma_f32_32x32x16_bf16 v[80:95], v[218:221], v[132:135], v[80:95]
	s_waitcnt lgkmcnt(4)
	v_mfma_f32_32x32x16_bf16 v[80:95], v[226:229], v[128:131], v[80:95]
	s_waitcnt lgkmcnt(3)
	v_mfma_f32_32x32x16_bf16 v[80:95], v[12:15], v[124:127], v[80:95]
	s_waitcnt lgkmcnt(2)
	v_mfma_f32_32x32x16_bf16 v[80:95], v[202:205], v[120:123], v[80:95]
	s_waitcnt lgkmcnt(1)
	v_mfma_f32_32x32x16_bf16 v[80:95], v[210:213], v[116:119], v[80:95]
	v_lshrrev_b32_e32 v0, v160, v10
	v_and_b32_e32 v0, 1, v0
	v_cmp_eq_u32_e32 vcc, 1, v0
	v_and_b32_e32 v0, 2, v8
	s_nop 0
	v_cndmask_b32_e32 v200, v225, v96, vcc
	v_cmp_ne_u32_e32 vcc, 0, v0
	v_and_b32_e32 v0, 4, v8
	s_waitcnt lgkmcnt(0)
	v_mfma_f32_32x32x16_bf16 v[80:95], v[214:217], v[112:115], v[80:95]
	v_cndmask_b32_e32 v187, v225, v97, vcc
	v_cmp_ne_u32_e32 vcc, 0, v0
	v_and_b32_e32 v0, 8, v8
	v_mbcnt_hi_u32_b32 v2, -1, v223
	v_cndmask_b32_e32 v199, v225, v98, vcc
	v_cmp_ne_u32_e32 vcc, 0, v0
	v_and_b32_e32 v0, 16, v8
	s_nop 0
	v_cndmask_b32_e32 v198, v225, v99, vcc
	v_cmp_ne_u32_e32 vcc, 0, v0
	v_and_b32_e32 v0, 32, v8
	s_nop 0
	v_cndmask_b32_e32 v201, v225, v100, vcc
	v_cmp_ne_u32_e32 vcc, 0, v0
	v_and_b32_e32 v0, 64, v8
	s_nop 0
	v_cndmask_b32_e32 v96, v225, v101, vcc
	v_cmp_ne_u32_e32 vcc, 0, v0
	v_and_b32_e32 v0, 0x80, v8
	s_nop 0
	v_cndmask_b32_e32 v186, v225, v102, vcc
	v_cmp_ne_u32_e32 vcc, 0, v0
	v_and_b32_e32 v0, 0x10000, v8
	s_nop 0
	v_cndmask_b32_e32 v97, v225, v103, vcc
	v_cmp_ne_u32_e32 vcc, 0, v0
	v_and_b32_e32 v0, 0x20000, v8
	s_nop 0
	v_cndmask_b32_e32 v185, v225, v104, vcc
	v_cmp_ne_u32_e32 vcc, 0, v0
	v_and_b32_e32 v0, 0x40000, v8
	s_nop 0
	v_cndmask_b32_e32 v105, v225, v105, vcc
	v_cmp_ne_u32_e32 vcc, 0, v0
	v_and_b32_e32 v0, 0x80000, v8
	s_nop 0
	v_cndmask_b32_e32 v104, v225, v106, vcc
	v_cmp_ne_u32_e32 vcc, 0, v0
	v_and_b32_e32 v0, 0x100000, v8
	s_nop 0
	v_cndmask_b32_e32 v103, v225, v107, vcc
	v_cmp_ne_u32_e32 vcc, 0, v0
	v_and_b32_e32 v0, 0x200000, v8
	s_nop 0
	v_cndmask_b32_e32 v102, v225, v108, vcc
	v_cmp_ne_u32_e32 vcc, 0, v0
	v_and_b32_e32 v0, 0x400000, v8
	s_nop 0
	v_cndmask_b32_e32 v10, v225, v109, vcc
	v_cmp_ne_u32_e32 vcc, 0, v0
	v_and_b32_e32 v0, 0x800000, v8
	s_nop 0
	v_cndmask_b32_e32 v100, v225, v110, vcc
	v_cmp_ne_u32_e32 vcc, 0, v0
	v_and_b32_e32 v0, 1, v9
	s_nop 0
	v_cndmask_b32_e32 v11, v225, v111, vcc
	v_cmp_eq_u32_e32 vcc, 1, v0
	v_and_b32_e32 v0, 2, v9
	s_nop 0
	v_cndmask_b32_e32 v101, v225, v80, vcc
	v_cmp_ne_u32_e32 vcc, 0, v0
	v_and_b32_e32 v0, 4, v9
	s_nop 0
	v_cndmask_b32_e32 v99, v225, v81, vcc
	v_cmp_ne_u32_e32 vcc, 0, v0
	v_and_b32_e32 v0, 8, v9
	s_nop 0
	v_cndmask_b32_e32 v12, v225, v82, vcc
	v_cmp_ne_u32_e32 vcc, 0, v0
	v_and_b32_e32 v0, 16, v9
	v_xor_b32_e32 v82, 32, v2
	v_cndmask_b32_e32 v13, v225, v83, vcc
	v_cmp_ne_u32_e32 vcc, 0, v0
	v_and_b32_e32 v0, 32, v9
	v_and_b32_e32 v83, 64, v2
	v_cndmask_b32_e32 v14, v225, v84, vcc
	v_cmp_ne_u32_e32 vcc, 0, v0
	v_and_b32_e32 v0, 64, v9
	v_add_u32_e32 v83, 64, v83
	v_cndmask_b32_e32 v15, v225, v85, vcc
	v_cmp_ne_u32_e32 vcc, 0, v0
	v_and_b32_e32 v0, 0x80, v9
	s_nop 0
	v_cndmask_b32_e32 v80, v225, v86, vcc
	v_cmp_ne_u32_e32 vcc, 0, v0
; template <int DQK, int MODE>
; DI void attn_core(const u16* __restrict__ Qg, int ldq, const u16* __restrict__ Kg, int ldk, const u16* __restrict__ Vtg,
;                   const u64* __restrict__ maskg, int q0, float scale, char* smem, int* sflags, f32x16 (&o)[4], float& l_run) {
;     ...
;   for (int it = 0; it < ntiles; ++it, tau += step) {
;     __syncthreads();
;     if (MODE == 2 && it > 0) {
;       if (!(sflags[0] | sflags[1] | sflags[2] | sflags[3] | sflags[4] | sflags[5] | sflags[6] | sflags[7])) break;
;     }
;     if (MODE == 2) gload(tau);
; #pragma unroll
;     for (int i = 0; i < NVK; ++i) {
;       const int v = tid + NT * i, row = v / VPR, c = v % VPR;
;       *(u32x4*)(Ks + row * KSTR + c * 8) = rk[i];
;     }
; #pragma unroll
;     for (int i = 0; i < 2; ++i) {
;       const int v = tid + NT * i, row = v >> 3, c = v & 7;
;       *(u32x4*)(Vs + row * 72 + c * 8) = rv[i];
;     }
;     __syncthreads();
;     ...
; #pragma unroll
;       for (int kt = 0; kt < 2; ++kt)
; #pragma unroll
;         for (int i = 0; i < 16; ++i) mx = fmaxf(mx, s[kt][i]);
;       mx = fmaxf(mx, __shfl_xor(mx, 32));
;       const float m_new = fmaxf(m_run, mx);
;       const float alpha = __builtin_amdgcn_exp2f((m_run - m_new) * sc);
;       m_run = m_new;
;       const float msc = -m_new * sc;
;       float ls = 0.f;
; #pragma unroll
;       for (int kt = 0; kt < 2; ++kt)
; #pragma unroll
;         for (int i = 0; i < 16; ++i) {
;           float pv = __builtin_amdgcn_exp2f(__builtin_fmaf(s[kt][i], sc, msc));
;           if (MODE == 1) pv = (s[kt][i] > -1e29f) ? pv : 0.f;
;           s[kt][i] = pv;
;           ls += pv;
;         }
;       if (__any(alpha != 1.0f)) {
;         l_run *= alpha;
; #pragma unroll
;         for (int t = 0; t < 4; ++t)
; #pragma unroll
;           for (int i = 0; i < 16; ++i) o[t][i] *= alpha;
;       }
	v_and_b32_e32 v0, 0x10000, v9
	s_nop 0
	v_cndmask_b32_e32 v81, v225, v87, vcc
	v_cmp_ne_u32_e32 vcc, 0, v0
	v_and_b32_e32 v0, 0x20000, v9
	s_nop 0
	v_cndmask_b32_e32 v98, v225, v88, vcc
	v_cmp_ne_u32_e32 vcc, 0, v0
	v_and_b32_e32 v0, 0x40000, v9
	s_nop 0
	v_cndmask_b32_e32 v3, v225, v89, vcc
	v_cmp_ne_u32_e32 vcc, 0, v0
	v_and_b32_e32 v0, 0x80000, v9
	s_nop 0
	v_cndmask_b32_e32 v4, v225, v90, vcc
	v_cmp_ne_u32_e32 vcc, 0, v0
	v_and_b32_e32 v0, 0x100000, v9
	s_nop 0
	v_cndmask_b32_e32 v5, v225, v91, vcc
	v_cmp_ne_u32_e32 vcc, 0, v0
	v_and_b32_e32 v0, 0x200000, v9
	s_nop 0
	v_cndmask_b32_e32 v6, v225, v92, vcc
	v_cmp_ne_u32_e32 vcc, 0, v0
	v_and_b32_e32 v0, 0x400000, v9
	s_nop 0
	v_cndmask_b32_e32 v7, v225, v93, vcc
	v_cmp_ne_u32_e32 vcc, 0, v0
	v_and_b32_e32 v0, 0x800000, v9
	s_nop 0
	v_cndmask_b32_e32 v8, v225, v94, vcc
	v_cmp_ne_u32_e32 vcc, 0, v0
	v_max3_f32 v0, v200, s58, v187
	v_max3_f32 v0, v0, v199, v198
	v_max3_f32 v0, v0, v201, v96
	v_max3_f32 v0, v0, v186, v97
	v_max3_f32 v0, v0, v185, v105
	v_max3_f32 v0, v0, v104, v103
	v_max3_f32 v0, v0, v102, v10
	v_max3_f32 v0, v0, v100, v11
	v_max3_f32 v0, v0, v101, v99
	v_max3_f32 v0, v0, v12, v13
	v_max3_f32 v0, v0, v14, v15
	v_max3_f32 v0, v0, v80, v81
	v_max3_f32 v0, v0, v98, v3
	v_cndmask_b32_e32 v9, v225, v95, vcc
	v_max3_f32 v0, v0, v4, v5
	v_cmp_lt_i32_e32 vcc, v82, v83
	v_max3_f32 v0, v0, v6, v7
	v_max3_f32 v0, v0, v8, v9
	v_cndmask_b32_e32 v2, v2, v82, vcc
	v_lshlrev_b32_e32 v2, 2, v2
	ds_bpermute_b32 v2, v2, v0
	s_waitcnt lgkmcnt(0)
	v_max3_f32 v2, v184, v0, v2
	v_sub_f32_e32 v0, v2, v184
	v_mul_f32_e32 v0, 0x3e0293ee, v0
	v_cmp_lt_f32_e32 vcc, 0x41000000, v0
	s_cbranch_vccnz .Llazy_keep_1
	v_mov_b32_e32 v2, v184
.Llazy_keep_1:
	v_sub_f32_e32 v0, v184, v2
	v_mul_f32_e32 v0, 0x3e0293ee, v0
	v_exp_f32_e32 v0, v0
	s_nop 0
	v_cmp_neq_f32_e32 vcc, 1.0, v0
	s_cbranch_vccz .LBB0_154
	v_mul_f32_e32 v161, v161, v0
	v_pk_mul_f32 v[78:79], v[0:1], v[78:79] op_sel_hi:[0,1]
	v_pk_mul_f32 v[76:77], v[0:1], v[76:77] op_sel_hi:[0,1]
	v_pk_mul_f32 v[74:75], v[0:1], v[74:75] op_sel_hi:[0,1]
	v_pk_mul_f32 v[72:73], v[0:1], v[72:73] op_sel_hi:[0,1]
	v_pk_mul_f32 v[70:71], v[0:1], v[70:71] op_sel_hi:[0,1]
	v_pk_mul_f32 v[68:69], v[0:1], v[68:69] op_sel_hi:[0,1]
	v_pk_mul_f32 v[66:67], v[0:1], v[66:67] op_sel_hi:[0,1]
	v_pk_mul_f32 v[64:65], v[0:1], v[64:65] op_sel_hi:[0,1]
	v_pk_mul_f32 v[62:63], v[0:1], v[62:63] op_sel_hi:[0,1]
	v_pk_mul_f32 v[60:61], v[0:1], v[60:61] op_sel_hi:[0,1]
	v_pk_mul_f32 v[58:59], v[0:1], v[58:59] op_sel_hi:[0,1]
	v_pk_mul_f32 v[56:57], v[0:1], v[56:57] op_sel_hi:[0,1]
	v_pk_mul_f32 v[54:55], v[0:1], v[54:55] op_sel_hi:[0,1]
	v_pk_mul_f32 v[52:53], v[0:1], v[52:53] op_sel_hi:[0,1]
	v_pk_mul_f32 v[50:51], v[0:1], v[50:51] op_sel_hi:[0,1]
	v_pk_mul_f32 v[48:49], v[0:1], v[48:49] op_sel_hi:[0,1]
	v_pk_mul_f32 v[46:47], v[0:1], v[46:47] op_sel_hi:[0,1]
	v_pk_mul_f32 v[44:45], v[0:1], v[44:45] op_sel_hi:[0,1]
	v_pk_mul_f32 v[42:43], v[0:1], v[42:43] op_sel_hi:[0,1]
	v_pk_mul_f32 v[40:41], v[0:1], v[40:41] op_sel_hi:[0,1]
	v_pk_mul_f32 v[38:39], v[0:1], v[38:39] op_sel_hi:[0,1]
	v_pk_mul_f32 v[36:37], v[0:1], v[36:37] op_sel_hi:[0,1]
	v_pk_mul_f32 v[34:35], v[0:1], v[34:35] op_sel_hi:[0,1]
	v_pk_mul_f32 v[32:33], v[0:1], v[32:33] op_sel_hi:[0,1]
	v_pk_mul_f32 v[30:31], v[0:1], v[30:31] op_sel_hi:[0,1]
	v_pk_mul_f32 v[28:29], v[0:1], v[28:29] op_sel_hi:[0,1]
	v_pk_mul_f32 v[26:27], v[0:1], v[26:27] op_sel_hi:[0,1]
	v_pk_mul_f32 v[24:25], v[0:1], v[24:25] op_sel_hi:[0,1]
	v_pk_mul_f32 v[22:23], v[0:1], v[22:23] op_sel_hi:[0,1]
	v_pk_mul_f32 v[20:21], v[0:1], v[20:21] op_sel_hi:[0,1]
	v_pk_mul_f32 v[18:19], v[0:1], v[18:19] op_sel_hi:[0,1]
	v_pk_mul_f32 v[16:17], v[0:1], v[16:17] op_sel_hi:[0,1]
	s_branch .LBB0_154
.LBB0_159:
	s_lshl_b32 s0, s14, 6
	v_cmp_le_i32_e32 vcc, s0, v179
	s_nop 0
	s_waitcnt vmcnt(3)
	ds_write_b128 v180, v[156:159]
	s_waitcnt vmcnt(2)
	ds_write_b128 v181, v[152:155]
	s_waitcnt vmcnt(1)
	ds_write_b128 v182, v[148:151] offset:17408
	s_waitcnt vmcnt(0)
	ds_write_b128 v183, v[144:147] offset:17408
	s_waitcnt lgkmcnt(0)
	s_barrier
	s_and_saveexec_b64 s[0:1], vcc
	s_xor_b64 s[0:1], exec, s[0:1]
	s_cbranch_execz .LBB0_164
	v_readlane_b32 s4, v249, 29
	v_readlane_b32 s5, v249, 30
	s_mov_b32 s15, s5
	s_add_i32 s14, s13, -2
	v_lshl_add_u64 v[2:3], s[14:15], 3, v[164:165]
	v_add_u32_e32 v0, v174, v178
	global_load_dwordx2 v[10:11], v[2:3], off offset:8
	ds_read_b128 v[12:15], v0
	ds_read_b128 v[144:147], v0 offset:32
	ds_read_b128 v[148:151], v0 offset:64
	ds_read_b128 v[152:155], v0 offset:96
	ds_read_b128 v[156:159], v0 offset:128
	ds_read_b128 v[162:165], v0 offset:160
	s_waitcnt lgkmcnt(5)
	v_mfma_f32_32x32x16_bf16 v[80:95], v[12:15], v[140:143], 0
	ds_read_b128 v[12:15], v0 offset:192
	v_writelane_b32 v249, s4, 29
	s_nop 1
	v_writelane_b32 v249, s5, 30
	s_waitcnt lgkmcnt(5)
	v_mfma_f32_32x32x16_bf16 v[80:95], v[144:147], v[136:139], v[80:95]
	ds_read_b128 v[144:147], v0 offset:224
	s_waitcnt lgkmcnt(5)
	v_mfma_f32_32x32x16_bf16 v[80:95], v[148:151], v[132:135], v[80:95]
	ds_read_b128 v[148:151], v0 offset:8704
	s_waitcnt lgkmcnt(5)
	v_mfma_f32_32x32x16_bf16 v[80:95], v[152:155], v[128:131], v[80:95]
	ds_read_b128 v[152:155], v0 offset:8736
	s_waitcnt lgkmcnt(5)
	v_mfma_f32_32x32x16_bf16 v[80:95], v[156:159], v[124:127], v[80:95]
	ds_read_b128 v[156:159], v0 offset:8768
	s_waitcnt lgkmcnt(5)
	v_mfma_f32_32x32x16_bf16 v[80:95], v[162:165], v[120:123], v[80:95]
	ds_read_b128 v[162:165], v0 offset:8800
	s_waitcnt lgkmcnt(5)
	v_mfma_f32_32x32x16_bf16 v[80:95], v[12:15], v[116:119], v[80:95]
	ds_read_b128 v[12:15], v0 offset:8832
	s_waitcnt lgkmcnt(5)
; #define MFMA32(a, b, c) __builtin_amdgcn_mfma_f32_32x32x16_bf16((a), (b), (c), 0, 0, 0)
; DI f32x16 zero16() { f32x16 z; for (int i = 0; i < 16; ++i) z[i] = 0.f; return z; }
; template <int DQK, int MODE>
; DI void attn_core(const u16* __restrict__ Qg, int ldq, const u16* __restrict__ Kg, int ldk, const u16* __restrict__ Vtg,
;                   const u64* __restrict__ maskg, int q0, float scale, char* smem, int* sflags, f32x16 (&o)[4], float& l_run) {
;     ...
;     u64 mbits = 0;
;     if (MODE == 1) mbits = maskg[(long)qrow * 64 + tau] >> (8 * hh);
;     f32x16 s[2];
;     s[0] = zero16(); s[1] = zero16();
; #pragma unroll
;     for (int kt = 0; kt < 2; ++kt)
; #pragma unroll
;       for (int ks = 0; ks < NKS; ++ks) {
;         const bf16x8 kf = *(const bf16x8*)(Ks + (32 * kt + krow) * KSTR + ks * 16 + hh * 8);
;         s[kt] = MFMA32(kf, qf[ks], s[kt]);
;       }
;     const int kbase = tau * 64 + 8 * hh;
;     if (MODE == 0 || MODE == 1) {
;       const bool need_mask = (MODE == 1) || (tau * 64 + 63 > q0 + 32 * wid);
;       float mx = -1e30f;
;       if (need_mask) {
; #pragma unroll
;         for (int kt = 0; kt < 2; ++kt)
; #pragma unroll
;           for (int i = 0; i < 16; ++i) {
;             bool valid;
;             if (MODE == 1) valid = (mbits >> (32 * kt + 16 * (i >> 3) + (i & 7))) & 1ull;
;             else valid = (kbase + 32 * kt + 16 * (i >> 3) + (i & 7)) <= qrow;
;             s[kt][i] = valid ? s[kt][i] : -1e30f;
;           }
;       }
; #pragma unroll
;       for (int kt = 0; kt < 2; ++kt)
; #pragma unroll
;         for (int i = 0; i < 16; ++i) mx = fmaxf(mx, s[kt][i]);
;       mx = fmaxf(mx, __shfl_xor(mx, 32));
;       const float m_new = fmaxf(m_run, mx);
;       const float alpha = __builtin_amdgcn_exp2f((m_run - m_new) * sc);
;       m_run = m_new;
	v_mfma_f32_32x32x16_bf16 v[80:95], v[144:147], v[112:115], v[80:95]
	ds_read_b128 v[144:147], v0 offset:8864
	s_waitcnt lgkmcnt(5)
	v_mfma_f32_32x32x16_bf16 v[96:111], v[148:151], v[140:143], 0
	ds_read_b128 v[148:151], v0 offset:8896
	s_waitcnt lgkmcnt(5)
	v_mfma_f32_32x32x16_bf16 v[96:111], v[152:155], v[136:139], v[96:111]
	ds_read_b128 v[152:155], v0 offset:8928
	s_waitcnt lgkmcnt(5)
	v_mfma_f32_32x32x16_bf16 v[96:111], v[156:159], v[132:135], v[96:111]
	s_waitcnt lgkmcnt(4)
	v_mfma_f32_32x32x16_bf16 v[96:111], v[162:165], v[128:131], v[96:111]
	s_waitcnt lgkmcnt(3)
	v_mfma_f32_32x32x16_bf16 v[96:111], v[12:15], v[124:127], v[96:111]
	s_waitcnt lgkmcnt(2)
	v_mfma_f32_32x32x16_bf16 v[96:111], v[144:147], v[120:123], v[96:111]
	s_waitcnt lgkmcnt(1)
	v_mfma_f32_32x32x16_bf16 v[96:111], v[148:151], v[116:119], v[96:111]
	s_waitcnt vmcnt(0)
	v_lshrrev_b32_e32 v0, v160, v10
	v_and_b32_e32 v0, 1, v0
	v_cmp_eq_u32_e32 vcc, 1, v0
	s_nop 1
	v_cndmask_b32_e32 v121, v225, v80, vcc
	s_waitcnt lgkmcnt(0)
	v_mfma_f32_32x32x16_bf16 v[96:111], v[152:155], v[112:115], v[96:111]
	v_lshrrev_b64 v[2:3], v160, v[10:11]
	v_and_b32_e32 v0, 2, v2
	v_cmp_ne_u32_e32 vcc, 0, v0
	v_and_b32_e32 v0, 4, v2
	s_nop 0
	v_cndmask_b32_e32 v118, v225, v81, vcc
	v_cmp_ne_u32_e32 vcc, 0, v0
	v_and_b32_e32 v0, 8, v2
	s_nop 0
	v_cndmask_b32_e32 v120, v225, v82, vcc
	v_cmp_ne_u32_e32 vcc, 0, v0
	v_and_b32_e32 v0, 16, v2
	s_nop 0
	v_cndmask_b32_e32 v119, v225, v83, vcc
	v_cmp_ne_u32_e32 vcc, 0, v0
	v_and_b32_e32 v0, 32, v2
	s_nop 0
	v_cndmask_b32_e32 v122, v225, v84, vcc
	v_cmp_ne_u32_e32 vcc, 0, v0
	v_and_b32_e32 v0, 64, v2
	s_nop 0
	v_cndmask_b32_e32 v116, v225, v85, vcc
	v_cmp_ne_u32_e32 vcc, 0, v0
	v_and_b32_e32 v0, 0x80, v2
	s_nop 0
	v_cndmask_b32_e32 v117, v225, v86, vcc
	v_cmp_ne_u32_e32 vcc, 0, v0
	v_and_b32_e32 v0, 0x10000, v2
	s_nop 0
	v_cndmask_b32_e32 v115, v225, v87, vcc
	v_cmp_ne_u32_e32 vcc, 0, v0
	v_and_b32_e32 v0, 0x20000, v2
	s_nop 0
	v_cndmask_b32_e32 v85, v225, v88, vcc
	v_cmp_ne_u32_e32 vcc, 0, v0
	v_and_b32_e32 v0, 0x40000, v2
	s_nop 0
	v_cndmask_b32_e32 v87, v225, v89, vcc
	v_cmp_ne_u32_e32 vcc, 0, v0
	v_and_b32_e32 v0, 0x80000, v2
	s_nop 0
	v_cndmask_b32_e32 v88, v225, v90, vcc
	v_cmp_ne_u32_e32 vcc, 0, v0
	v_and_b32_e32 v0, 0x100000, v2
	s_nop 0
	v_cndmask_b32_e32 v91, v225, v91, vcc
	v_cmp_ne_u32_e32 vcc, 0, v0
	v_and_b32_e32 v0, 0x200000, v2
	s_nop 0
	v_cndmask_b32_e32 v92, v225, v92, vcc
	v_cmp_ne_u32_e32 vcc, 0, v0
	v_and_b32_e32 v0, 0x400000, v2
	s_nop 0
	v_cndmask_b32_e32 v13, v225, v93, vcc
	v_cmp_ne_u32_e32 vcc, 0, v0
	v_and_b32_e32 v0, 0x800000, v2
	v_mbcnt_hi_u32_b32 v2, -1, v223
	v_cndmask_b32_e32 v113, v225, v94, vcc
	v_cmp_ne_u32_e32 vcc, 0, v0
	v_and_b32_e32 v0, 1, v3
	v_and_b32_e32 v4, 64, v2
	v_cndmask_b32_e32 v14, v225, v95, vcc
	v_cmp_eq_u32_e32 vcc, 1, v0
	v_and_b32_e32 v0, 2, v3
	v_add_u32_e32 v4, 64, v4
	v_cndmask_b32_e32 v114, v225, v96, vcc
	v_cmp_ne_u32_e32 vcc, 0, v0
	v_and_b32_e32 v0, 4, v3
	s_nop 0
	v_cndmask_b32_e32 v112, v225, v97, vcc
	v_cmp_ne_u32_e32 vcc, 0, v0
	v_and_b32_e32 v0, 8, v3
	s_nop 0
	v_cndmask_b32_e32 v15, v225, v98, vcc
	v_cmp_ne_u32_e32 vcc, 0, v0
	v_and_b32_e32 v0, 16, v3
	s_nop 0
	v_cndmask_b32_e32 v80, v225, v99, vcc
	v_cmp_ne_u32_e32 vcc, 0, v0
	v_and_b32_e32 v0, 32, v3
	s_nop 0
	v_cndmask_b32_e32 v81, v225, v100, vcc
	v_cmp_ne_u32_e32 vcc, 0, v0
	v_and_b32_e32 v0, 64, v3
	s_nop 0
	v_cndmask_b32_e32 v82, v225, v101, vcc
	v_cmp_ne_u32_e32 vcc, 0, v0
	v_and_b32_e32 v0, 0x80, v3
	s_nop 0
	v_cndmask_b32_e32 v83, v225, v102, vcc
	v_cmp_ne_u32_e32 vcc, 0, v0
	v_and_b32_e32 v0, 0x10000, v3
	s_nop 0
	v_cndmask_b32_e32 v84, v225, v103, vcc
	v_cmp_ne_u32_e32 vcc, 0, v0
	v_and_b32_e32 v0, 0x20000, v3
	s_nop 0
	v_cndmask_b32_e32 v5, v225, v104, vcc
	v_cmp_ne_u32_e32 vcc, 0, v0
	v_and_b32_e32 v0, 0x40000, v3
	s_nop 0
	v_cndmask_b32_e32 v6, v225, v105, vcc
	v_cmp_ne_u32_e32 vcc, 0, v0
	v_and_b32_e32 v0, 0x80000, v3
	s_nop 0
	v_cndmask_b32_e32 v7, v225, v106, vcc
	v_cmp_ne_u32_e32 vcc, 0, v0
	v_and_b32_e32 v0, 0x100000, v3
	s_nop 0
	v_cndmask_b32_e32 v8, v225, v107, vcc
	v_cmp_ne_u32_e32 vcc, 0, v0
	v_and_b32_e32 v0, 0x200000, v3
	s_nop 0
	v_cndmask_b32_e32 v9, v225, v108, vcc
	v_cmp_ne_u32_e32 vcc, 0, v0
	v_and_b32_e32 v0, 0x400000, v3
	s_nop 0
	v_cndmask_b32_e32 v10, v225, v109, vcc
	v_cmp_ne_u32_e32 vcc, 0, v0
	v_and_b32_e32 v0, 0x800000, v3
	v_xor_b32_e32 v3, 32, v2
	v_cndmask_b32_e32 v11, v225, v110, vcc
	v_cmp_ne_u32_e32 vcc, 0, v0
	v_max3_f32 v0, v121, s58, v118
	v_max3_f32 v0, v0, v120, v119
	v_max3_f32 v0, v0, v122, v116
	v_max3_f32 v0, v0, v117, v115
	v_max3_f32 v0, v0, v85, v87
	v_max3_f32 v0, v0, v88, v91
	v_max3_f32 v0, v0, v92, v13
	v_max3_f32 v0, v0, v113, v14
	v_max3_f32 v0, v0, v114, v112
	v_max3_f32 v0, v0, v15, v80
	v_max3_f32 v0, v0, v81, v82
	v_max3_f32 v0, v0, v83, v84
	v_max3_f32 v0, v0, v5, v6
	v_cndmask_b32_e32 v12, v225, v111, vcc
	v_max3_f32 v0, v0, v7, v8
	v_cmp_lt_i32_e32 vcc, v3, v4
	v_max3_f32 v0, v0, v9, v10
	v_max3_f32 v0, v0, v11, v12
	v_cndmask_b32_e32 v86, v2, v3, vcc
	v_lshlrev_b32_e32 v86, 2, v86
	ds_bpermute_b32 v86, v86, v0
	s_waitcnt lgkmcnt(0)
	v_max3_f32 v86, v184, v0, v86
	v_sub_f32_e32 v0, v86, v184
	v_mul_f32_e32 v0, 0x3e0293ee, v0
	v_cmp_lt_f32_e32 vcc, 0x41000000, v0
	s_cbranch_vccnz .Llazy_keep_2
	v_mov_b32_e32 v86, v184
; template <int DQK, int MODE>
; DI void attn_core(const u16* __restrict__ Qg, int ldq, const u16* __restrict__ Kg, int ldk, const u16* __restrict__ Vtg,
;                   const u64* __restrict__ maskg, int q0, float scale, char* smem, int* sflags, f32x16 (&o)[4], float& l_run) {
;     ...
;       const float m_new = fmaxf(m_run, mx);
;       const float alpha = __builtin_amdgcn_exp2f((m_run - m_new) * sc);
;       m_run = m_new;
;       const float msc = -m_new * sc;
;       float ls = 0.f;
; #pragma unroll
;       for (int kt = 0; kt < 2; ++kt)
; #pragma unroll
;         for (int i = 0; i < 16; ++i) {
;           float pv = __builtin_amdgcn_exp2f(__builtin_fmaf(s[kt][i], sc, msc));
;           if (MODE == 1) pv = (s[kt][i] > -1e29f) ? pv : 0.f;
;           s[kt][i] = pv;
;           ls += pv;
;         }
;       if (__any(alpha != 1.0f)) {
;         l_run *= alpha;
; #pragma unroll
;         for (int t = 0; t < 4; ++t)
; #pragma unroll
;           for (int i = 0; i < 16; ++i) o[t][i] *= alpha;
;       }
.Llazy_keep_2:
	v_sub_f32_e32 v0, v184, v86
	v_mul_f32_e32 v0, 0x3e0293ee, v0
	v_exp_f32_e32 v0, v0
	s_nop 0
	v_cmp_neq_f32_e32 vcc, 1.0, v0
	s_cbranch_vccz .LBB0_162
	v_mul_f32_e32 v101, v161, v0
	v_pk_mul_f32 v[78:79], v[0:1], v[78:79] op_sel_hi:[0,1]
	v_pk_mul_f32 v[76:77], v[0:1], v[76:77] op_sel_hi:[0,1]
	v_pk_mul_f32 v[74:75], v[0:1], v[74:75] op_sel_hi:[0,1]
	v_pk_mul_f32 v[72:73], v[0:1], v[72:73] op_sel_hi:[0,1]
	v_pk_mul_f32 v[70:71], v[0:1], v[70:71] op_sel_hi:[0,1]
	v_pk_mul_f32 v[68:69], v[0:1], v[68:69] op_sel_hi:[0,1]
	v_pk_mul_f32 v[66:67], v[0:1], v[66:67] op_sel_hi:[0,1]
	v_pk_mul_f32 v[64:65], v[0:1], v[64:65] op_sel_hi:[0,1]
	v_pk_mul_f32 v[62:63], v[0:1], v[62:63] op_sel_hi:[0,1]
	v_pk_mul_f32 v[60:61], v[0:1], v[60:61] op_sel_hi:[0,1]
	v_pk_mul_f32 v[58:59], v[0:1], v[58:59] op_sel_hi:[0,1]
	v_pk_mul_f32 v[56:57], v[0:1], v[56:57] op_sel_hi:[0,1]
	v_pk_mul_f32 v[54:55], v[0:1], v[54:55] op_sel_hi:[0,1]
	v_pk_mul_f32 v[52:53], v[0:1], v[52:53] op_sel_hi:[0,1]
	v_pk_mul_f32 v[50:51], v[0:1], v[50:51] op_sel_hi:[0,1]
	v_pk_mul_f32 v[48:49], v[0:1], v[48:49] op_sel_hi:[0,1]
	v_pk_mul_f32 v[46:47], v[0:1], v[46:47] op_sel_hi:[0,1]
	v_pk_mul_f32 v[44:45], v[0:1], v[44:45] op_sel_hi:[0,1]
	v_pk_mul_f32 v[42:43], v[0:1], v[42:43] op_sel_hi:[0,1]
	v_pk_mul_f32 v[40:41], v[0:1], v[40:41] op_sel_hi:[0,1]
	v_pk_mul_f32 v[38:39], v[0:1], v[38:39] op_sel_hi:[0,1]
	v_pk_mul_f32 v[36:37], v[0:1], v[36:37] op_sel_hi:[0,1]
	v_pk_mul_f32 v[34:35], v[0:1], v[34:35] op_sel_hi:[0,1]
	v_pk_mul_f32 v[32:33], v[0:1], v[32:33] op_sel_hi:[0,1]
	v_pk_mul_f32 v[30:31], v[0:1], v[30:31] op_sel_hi:[0,1]
	v_pk_mul_f32 v[28:29], v[0:1], v[28:29] op_sel_hi:[0,1]
	v_pk_mul_f32 v[26:27], v[0:1], v[26:27] op_sel_hi:[0,1]
	v_pk_mul_f32 v[24:25], v[0:1], v[24:25] op_sel_hi:[0,1]
	v_pk_mul_f32 v[22:23], v[0:1], v[22:23] op_sel_hi:[0,1]
	v_pk_mul_f32 v[20:21], v[0:1], v[20:21] op_sel_hi:[0,1]
	v_pk_mul_f32 v[18:19], v[0:1], v[18:19] op_sel_hi:[0,1]
	v_pk_mul_f32 v[16:17], v[0:1], v[16:17] op_sel_hi:[0,1]
	s_branch .LBB0_163

; template <int DQK, int MODE>
; DI void attn_core(const u16* __restrict__ Qg, int ldq, const u16* __restrict__ Kg, int ldk, const u16* __restrict__ Vtg,
;                   const u64* __restrict__ maskg, int q0, float scale, char* smem, int* sflags, f32x16 (&o)[4], float& l_run) {
;     ...
; #pragma unroll
;       for (int kt = 0; kt < 2; ++kt)
; #pragma unroll
;         for (int i = 0; i < 16; ++i) mx = fmaxf(mx, s[kt][i]);
;       mx = fmaxf(mx, __shfl_xor(mx, 32));
;       const float m_new = fmaxf(m_run, mx);
;       const float alpha = __builtin_amdgcn_exp2f((m_run - m_new) * sc);
;       m_run = m_new;
;       const float msc = -m_new * sc;
;       float ls = 0.f;
; #pragma unroll
;       for (int kt = 0; kt < 2; ++kt)
; #pragma unroll
;         for (int i = 0; i < 16; ++i) {
;           float pv = __builtin_amdgcn_exp2f(__builtin_fmaf(s[kt][i], sc, msc));
;           if (MODE == 1) pv = (s[kt][i] > -1e29f) ? pv : 0.f;
;           s[kt][i] = pv;
;           ls += pv;
;         }
;       if (__any(alpha != 1.0f)) {
;         l_run *= alpha;
; #pragma unroll
;         for (int t = 0; t < 4; ++t)
; #pragma unroll
;           for (int i = 0; i < 16; ++i) o[t][i] *= alpha;
;       }
.LBB0_172:
	s_or_b64 exec, exec, s[6:7]
	v_max3_f32 v0, v80, s58, v81
	v_max3_f32 v0, v0, v82, v83
	v_max3_f32 v0, v0, v84, v85
	v_max3_f32 v0, v0, v86, v87
	v_max3_f32 v0, v0, v88, v89
	v_max3_f32 v0, v0, v90, v91
	v_max3_f32 v0, v0, v92, v93
	v_max3_f32 v0, v0, v94, v95
	s_nop 0
	v_max3_f32 v0, v0, v96, v97
	v_max3_f32 v0, v0, v98, v99
	v_max3_f32 v0, v0, v100, v101
	v_mbcnt_hi_u32_b32 v2, -1, v223
	v_max3_f32 v0, v0, v102, v103
	v_and_b32_e32 v4, 64, v2
	v_max3_f32 v0, v0, v104, v105
	v_xor_b32_e32 v3, 32, v2
	v_add_u32_e32 v4, 64, v4
	v_max3_f32 v0, v0, v106, v107
	v_cmp_lt_i32_e32 vcc, v3, v4
	v_max3_f32 v0, v0, v108, v109
	v_max3_f32 v0, v0, v110, v111
	v_cndmask_b32_e32 v2, v2, v3, vcc
	v_lshlrev_b32_e32 v2, 2, v2
	ds_bpermute_b32 v2, v2, v0
	s_waitcnt lgkmcnt(0)
	v_max3_f32 v2, v230, v0, v2
	v_sub_f32_e32 v0, v2, v230
	v_mul_f32_e32 v0, 0x3dd53b94, v0
	v_cmp_lt_f32_e32 vcc, 0x41000000, v0
	s_cbranch_vccnz .Llazy_keep_3
	v_mov_b32_e32 v2, v230
.Llazy_keep_3:
	v_sub_f32_e32 v0, v230, v2
	v_mul_f32_e32 v0, 0x3dd53b94, v0
	v_exp_f32_e32 v0, v0
	s_nop 0
	v_cmp_neq_f32_e32 vcc, 1.0, v0
	s_cbranch_vccz .LBB0_174
	v_mul_f32_e32 v210, v210, v0
	v_pk_mul_f32 v[78:79], v[0:1], v[78:79] op_sel_hi:[0,1]
	v_pk_mul_f32 v[76:77], v[0:1], v[76:77] op_sel_hi:[0,1]
	v_pk_mul_f32 v[74:75], v[0:1], v[74:75] op_sel_hi:[0,1]
	v_pk_mul_f32 v[72:73], v[0:1], v[72:73] op_sel_hi:[0,1]
	v_pk_mul_f32 v[70:71], v[0:1], v[70:71] op_sel_hi:[0,1]
	v_pk_mul_f32 v[68:69], v[0:1], v[68:69] op_sel_hi:[0,1]
	v_pk_mul_f32 v[66:67], v[0:1], v[66:67] op_sel_hi:[0,1]
	v_pk_mul_f32 v[64:65], v[0:1], v[64:65] op_sel_hi:[0,1]
	v_pk_mul_f32 v[62:63], v[0:1], v[62:63] op_sel_hi:[0,1]
	v_pk_mul_f32 v[60:61], v[0:1], v[60:61] op_sel_hi:[0,1]
	v_pk_mul_f32 v[58:59], v[0:1], v[58:59] op_sel_hi:[0,1]
	v_pk_mul_f32 v[56:57], v[0:1], v[56:57] op_sel_hi:[0,1]
	v_pk_mul_f32 v[54:55], v[0:1], v[54:55] op_sel_hi:[0,1]
	v_pk_mul_f32 v[52:53], v[0:1], v[52:53] op_sel_hi:[0,1]
	v_pk_mul_f32 v[50:51], v[0:1], v[50:51] op_sel_hi:[0,1]
	v_pk_mul_f32 v[48:49], v[0:1], v[48:49] op_sel_hi:[0,1]
	v_pk_mul_f32 v[46:47], v[0:1], v[46:47] op_sel_hi:[0,1]
	v_pk_mul_f32 v[44:45], v[0:1], v[44:45] op_sel_hi:[0,1]
	v_pk_mul_f32 v[42:43], v[0:1], v[42:43] op_sel_hi:[0,1]
	v_pk_mul_f32 v[40:41], v[0:1], v[40:41] op_sel_hi:[0,1]
	v_pk_mul_f32 v[38:39], v[0:1], v[38:39] op_sel_hi:[0,1]
	v_pk_mul_f32 v[36:37], v[0:1], v[36:37] op_sel_hi:[0,1]
	v_pk_mul_f32 v[34:35], v[0:1], v[34:35] op_sel_hi:[0,1]
	v_pk_mul_f32 v[32:33], v[0:1], v[32:33] op_sel_hi:[0,1]
	v_pk_mul_f32 v[30:31], v[0:1], v[30:31] op_sel_hi:[0,1]
	v_pk_mul_f32 v[28:29], v[0:1], v[28:29] op_sel_hi:[0,1]
	v_pk_mul_f32 v[26:27], v[0:1], v[26:27] op_sel_hi:[0,1]
	v_pk_mul_f32 v[24:25], v[0:1], v[24:25] op_sel_hi:[0,1]
	v_pk_mul_f32 v[22:23], v[0:1], v[22:23] op_sel_hi:[0,1]
	v_pk_mul_f32 v[20:21], v[0:1], v[20:21] op_sel_hi:[0,1]
	v_pk_mul_f32 v[18:19], v[0:1], v[18:19] op_sel_hi:[0,1]
	v_pk_mul_f32 v[16:17], v[0:1], v[16:17] op_sel_hi:[0,1]

; template <int DQK, int MODE>
; DI void attn_core(const u16* __restrict__ Qg, int ldq, const u16* __restrict__ Kg, int ldk, const u16* __restrict__ Vtg,
;                   const u64* __restrict__ maskg, int q0, float scale, char* smem, int* sflags, f32x16 (&o)[4], float& l_run) {
;     ...
; #pragma unroll
;       for (int kt = 0; kt < 2; ++kt)
; #pragma unroll
;         for (int i = 0; i < 16; ++i) mx = fmaxf(mx, s[kt][i]);
;       mx = fmaxf(mx, __shfl_xor(mx, 32));
;       const float m_new = fmaxf(m_run, mx);
;       const float alpha = __builtin_amdgcn_exp2f((m_run - m_new) * sc);
;       m_run = m_new;
;       const float msc = -m_new * sc;
;       float ls = 0.f;
; #pragma unroll
;       for (int kt = 0; kt < 2; ++kt)
; #pragma unroll
;         for (int i = 0; i < 16; ++i) {
;           float pv = __builtin_amdgcn_exp2f(__builtin_fmaf(s[kt][i], sc, msc));
;           if (MODE == 1) pv = (s[kt][i] > -1e29f) ? pv : 0.f;
;           s[kt][i] = pv;
;           ls += pv;
;         }
;       if (__any(alpha != 1.0f)) {
;         l_run *= alpha;
; #pragma unroll
;         for (int t = 0; t < 4; ++t)
; #pragma unroll
;           for (int i = 0; i < 16; ++i) o[t][i] *= alpha;
;       }
.LBB0_180:
	s_or_b64 exec, exec, s[4:5]
	v_max3_f32 v0, v80, s58, v81
	v_max3_f32 v0, v0, v82, v83
	v_max3_f32 v0, v0, v84, v85
	v_max3_f32 v0, v0, v86, v87
	v_max3_f32 v0, v0, v88, v89
	v_max3_f32 v0, v0, v90, v91
	v_max3_f32 v0, v0, v92, v93
	v_max3_f32 v0, v0, v94, v95
	s_nop 0
	v_max3_f32 v0, v0, v96, v97
	v_max3_f32 v0, v0, v98, v99
	v_max3_f32 v0, v0, v100, v101
	v_mbcnt_hi_u32_b32 v2, -1, v223
	v_max3_f32 v0, v0, v102, v103
	v_and_b32_e32 v4, 64, v2
	v_max3_f32 v0, v0, v104, v105
	v_xor_b32_e32 v3, 32, v2
	v_add_u32_e32 v4, 64, v4
	v_max3_f32 v0, v0, v106, v107
	v_cmp_lt_i32_e32 vcc, v3, v4
	v_max3_f32 v0, v0, v108, v109
	v_max3_f32 v0, v0, v110, v111
	v_cndmask_b32_e32 v5, v2, v3, vcc
	v_lshlrev_b32_e32 v5, 2, v5
	ds_bpermute_b32 v5, v5, v0
	s_waitcnt lgkmcnt(0)
	v_max3_f32 v5, v230, v0, v5
	v_sub_f32_e32 v0, v5, v230
	v_mul_f32_e32 v0, 0x3dd53b94, v0
	v_cmp_lt_f32_e32 vcc, 0x41000000, v0
	s_cbranch_vccnz .Llazy_keep_4
	v_mov_b32_e32 v5, v230
.Llazy_keep_4:
	v_sub_f32_e32 v0, v230, v5
	v_mul_f32_e32 v0, 0x3dd53b94, v0
	v_exp_f32_e32 v0, v0
	s_nop 0
	v_cmp_neq_f32_e32 vcc, 1.0, v0
	s_cbranch_vccz .LBB0_182
	v_mul_f32_e32 v112, v210, v0
	v_pk_mul_f32 v[78:79], v[0:1], v[78:79] op_sel_hi:[0,1]
	v_pk_mul_f32 v[76:77], v[0:1], v[76:77] op_sel_hi:[0,1]
	v_pk_mul_f32 v[74:75], v[0:1], v[74:75] op_sel_hi:[0,1]
	v_pk_mul_f32 v[72:73], v[0:1], v[72:73] op_sel_hi:[0,1]
	v_pk_mul_f32 v[70:71], v[0:1], v[70:71] op_sel_hi:[0,1]
	v_pk_mul_f32 v[68:69], v[0:1], v[68:69] op_sel_hi:[0,1]
	v_pk_mul_f32 v[66:67], v[0:1], v[66:67] op_sel_hi:[0,1]
	v_pk_mul_f32 v[64:65], v[0:1], v[64:65] op_sel_hi:[0,1]
	v_pk_mul_f32 v[62:63], v[0:1], v[62:63] op_sel_hi:[0,1]
	v_pk_mul_f32 v[60:61], v[0:1], v[60:61] op_sel_hi:[0,1]
	v_pk_mul_f32 v[58:59], v[0:1], v[58:59] op_sel_hi:[0,1]
	v_pk_mul_f32 v[56:57], v[0:1], v[56:57] op_sel_hi:[0,1]
	v_pk_mul_f32 v[54:55], v[0:1], v[54:55] op_sel_hi:[0,1]
	v_pk_mul_f32 v[52:53], v[0:1], v[52:53] op_sel_hi:[0,1]
	v_pk_mul_f32 v[50:51], v[0:1], v[50:51] op_sel_hi:[0,1]
	v_pk_mul_f32 v[48:49], v[0:1], v[48:49] op_sel_hi:[0,1]
	v_pk_mul_f32 v[46:47], v[0:1], v[46:47] op_sel_hi:[0,1]
	v_pk_mul_f32 v[44:45], v[0:1], v[44:45] op_sel_hi:[0,1]
	v_pk_mul_f32 v[42:43], v[0:1], v[42:43] op_sel_hi:[0,1]
	v_pk_mul_f32 v[40:41], v[0:1], v[40:41] op_sel_hi:[0,1]
	v_pk_mul_f32 v[38:39], v[0:1], v[38:39] op_sel_hi:[0,1]
	v_pk_mul_f32 v[36:37], v[0:1], v[36:37] op_sel_hi:[0,1]
	v_pk_mul_f32 v[34:35], v[0:1], v[34:35] op_sel_hi:[0,1]
	v_pk_mul_f32 v[32:33], v[0:1], v[32:33] op_sel_hi:[0,1]
	v_pk_mul_f32 v[30:31], v[0:1], v[30:31] op_sel_hi:[0,1]
	v_pk_mul_f32 v[28:29], v[0:1], v[28:29] op_sel_hi:[0,1]
	v_pk_mul_f32 v[26:27], v[0:1], v[26:27] op_sel_hi:[0,1]
	v_pk_mul_f32 v[24:25], v[0:1], v[24:25] op_sel_hi:[0,1]
	v_pk_mul_f32 v[22:23], v[0:1], v[22:23] op_sel_hi:[0,1]
	v_pk_mul_f32 v[20:21], v[0:1], v[20:21] op_sel_hi:[0,1]
	v_pk_mul_f32 v[18:19], v[0:1], v[18:19] op_sel_hi:[0,1]
	v_pk_mul_f32 v[16:17], v[0:1], v[16:17] op_sel_hi:[0,1]
	s_branch .LBB0_183

; template <int DQK, int MODE>
; DI void attn_core(const u16* __restrict__ Qg, int ldq, const u16* __restrict__ Kg, int ldk, const u16* __restrict__ Vtg,
;                   const u64* __restrict__ maskg, int q0, float scale, char* smem, int* sflags, f32x16 (&o)[4], float& l_run) {
;     ...
; #pragma unroll
;       for (int kt = 0; kt < 2; ++kt)
; #pragma unroll
;         for (int i = 0; i < 16; ++i) mx = fmaxf(mx, s[kt][i]);
;       mx = fmaxf(mx, __shfl_xor(mx, 32));
;       const float m_new = fmaxf(m_run, mx);
;       const float alpha = __builtin_amdgcn_exp2f((m_run - m_new) * sc);
;       m_run = m_new;
;       const float msc = -m_new * sc;
;       float ls = 0.f;
; #pragma unroll
;       for (int kt = 0; kt < 2; ++kt)
; #pragma unroll
;         for (int i = 0; i < 16; ++i) {
;           float pv = __builtin_amdgcn_exp2f(__builtin_fmaf(s[kt][i], sc, msc));
;           if (MODE == 1) pv = (s[kt][i] > -1e29f) ? pv : 0.f;
;           s[kt][i] = pv;
;           ls += pv;
;         }
;       if (__any(alpha != 1.0f)) {
;         l_run *= alpha;
; #pragma unroll
;         for (int t = 0; t < 4; ++t)
; #pragma unroll
;           for (int i = 0; i < 16; ++i) o[t][i] *= alpha;
;       }
.LBB0_243:
	s_or_b64 exec, exec, s[8:9]
	v_max3_f32 v0, v96, s58, v97
	v_max3_f32 v0, v0, v98, v99
	v_max3_f32 v0, v0, v100, v101
	v_max3_f32 v0, v0, v102, v103
	v_max3_f32 v0, v0, v104, v105
	v_max3_f32 v0, v0, v106, v107
	v_max3_f32 v0, v0, v108, v109
	v_max3_f32 v0, v0, v110, v111
	s_nop 0
	v_max3_f32 v0, v0, v80, v81
	v_max3_f32 v0, v0, v82, v83
	v_max3_f32 v0, v0, v84, v85
	v_mbcnt_hi_u32_b32 v2, -1, v223
	v_max3_f32 v0, v0, v86, v87
	v_and_b32_e32 v4, 64, v2
	v_max3_f32 v0, v0, v88, v89
	v_xor_b32_e32 v3, 32, v2
	v_add_u32_e32 v4, 64, v4
	v_max3_f32 v0, v0, v90, v91
	v_cmp_lt_i32_e32 vcc, v3, v4
	v_max3_f32 v0, v0, v92, v93
	v_max3_f32 v0, v0, v94, v95
	v_cndmask_b32_e32 v2, v2, v3, vcc
	v_lshlrev_b32_e32 v2, 2, v2
	ds_bpermute_b32 v2, v2, v0
	s_waitcnt lgkmcnt(0)
	v_max3_f32 v2, v160, v0, v2
	v_sub_f32_e32 v0, v2, v160
	v_mul_f32_e32 v0, 0x3e38aa3b, v0
	v_cmp_lt_f32_e32 vcc, 0x41000000, v0
	s_cbranch_vccnz .Llazy_keep_5
	v_mov_b32_e32 v2, v160
.Llazy_keep_5:
	v_sub_f32_e32 v0, v160, v2
	v_mul_f32_e32 v0, 0x3e38aa3b, v0
	v_exp_f32_e32 v0, v0
	s_nop 0
	v_cmp_neq_f32_e32 vcc, 1.0, v0
	s_cbranch_vccz .LBB0_245
	v_mul_f32_e32 v148, v148, v0
	v_pk_mul_f32 v[78:79], v[0:1], v[78:79] op_sel_hi:[0,1]
	v_pk_mul_f32 v[76:77], v[0:1], v[76:77] op_sel_hi:[0,1]
	v_pk_mul_f32 v[74:75], v[0:1], v[74:75] op_sel_hi:[0,1]
	v_pk_mul_f32 v[72:73], v[0:1], v[72:73] op_sel_hi:[0,1]
	v_pk_mul_f32 v[70:71], v[0:1], v[70:71] op_sel_hi:[0,1]
	v_pk_mul_f32 v[68:69], v[0:1], v[68:69] op_sel_hi:[0,1]
	v_pk_mul_f32 v[66:67], v[0:1], v[66:67] op_sel_hi:[0,1]
	v_pk_mul_f32 v[64:65], v[0:1], v[64:65] op_sel_hi:[0,1]
	v_pk_mul_f32 v[62:63], v[0:1], v[62:63] op_sel_hi:[0,1]
	v_pk_mul_f32 v[60:61], v[0:1], v[60:61] op_sel_hi:[0,1]
	v_pk_mul_f32 v[58:59], v[0:1], v[58:59] op_sel_hi:[0,1]
	v_pk_mul_f32 v[56:57], v[0:1], v[56:57] op_sel_hi:[0,1]
	v_pk_mul_f32 v[54:55], v[0:1], v[54:55] op_sel_hi:[0,1]
	v_pk_mul_f32 v[52:53], v[0:1], v[52:53] op_sel_hi:[0,1]
	v_pk_mul_f32 v[50:51], v[0:1], v[50:51] op_sel_hi:[0,1]
	v_pk_mul_f32 v[48:49], v[0:1], v[48:49] op_sel_hi:[0,1]
	v_pk_mul_f32 v[46:47], v[0:1], v[46:47] op_sel_hi:[0,1]
	v_pk_mul_f32 v[44:45], v[0:1], v[44:45] op_sel_hi:[0,1]
	v_pk_mul_f32 v[42:43], v[0:1], v[42:43] op_sel_hi:[0,1]
	v_pk_mul_f32 v[40:41], v[0:1], v[40:41] op_sel_hi:[0,1]
	v_pk_mul_f32 v[38:39], v[0:1], v[38:39] op_sel_hi:[0,1]
	v_pk_mul_f32 v[36:37], v[0:1], v[36:37] op_sel_hi:[0,1]
	v_pk_mul_f32 v[34:35], v[0:1], v[34:35] op_sel_hi:[0,1]
	v_pk_mul_f32 v[32:33], v[0:1], v[32:33] op_sel_hi:[0,1]
	v_pk_mul_f32 v[30:31], v[0:1], v[30:31] op_sel_hi:[0,1]
	v_pk_mul_f32 v[28:29], v[0:1], v[28:29] op_sel_hi:[0,1]
	v_pk_mul_f32 v[26:27], v[0:1], v[26:27] op_sel_hi:[0,1]
	v_pk_mul_f32 v[24:25], v[0:1], v[24:25] op_sel_hi:[0,1]
	v_pk_mul_f32 v[22:23], v[0:1], v[22:23] op_sel_hi:[0,1]
	v_pk_mul_f32 v[20:21], v[0:1], v[20:21] op_sel_hi:[0,1]
	v_pk_mul_f32 v[18:19], v[0:1], v[18:19] op_sel_hi:[0,1]
	v_pk_mul_f32 v[16:17], v[0:1], v[16:17] op_sel_hi:[0,1]

; template <int DQK, int MODE>
; DI void attn_core(const u16* __restrict__ Qg, int ldq, const u16* __restrict__ Kg, int ldk, const u16* __restrict__ Vtg,
;                   const u64* __restrict__ maskg, int q0, float scale, char* smem, int* sflags, f32x16 (&o)[4], float& l_run) {
;     ...
; #pragma unroll
;       for (int kt = 0; kt < 2; ++kt)
; #pragma unroll
;         for (int i = 0; i < 16; ++i) mx = fmaxf(mx, s[kt][i]);
;       mx = fmaxf(mx, __shfl_xor(mx, 32));
;       const float m_new = fmaxf(m_run, mx);
;       const float alpha = __builtin_amdgcn_exp2f((m_run - m_new) * sc);
;       m_run = m_new;
;       const float msc = -m_new * sc;
;       float ls = 0.f;
; #pragma unroll
;       for (int kt = 0; kt < 2; ++kt)
; #pragma unroll
;         for (int i = 0; i < 16; ++i) {
;           float pv = __builtin_amdgcn_exp2f(__builtin_fmaf(s[kt][i], sc, msc));
;           if (MODE == 1) pv = (s[kt][i] > -1e29f) ? pv : 0.f;
;           s[kt][i] = pv;
;           ls += pv;
;         }
;       if (__any(alpha != 1.0f)) {
;         l_run *= alpha;
; #pragma unroll
;         for (int t = 0; t < 4; ++t)
; #pragma unroll
;           for (int i = 0; i < 16; ++i) o[t][i] *= alpha;
;       }
.LBB0_251:
	s_or_b64 exec, exec, s[6:7]
	v_max3_f32 v0, v96, s58, v97
	v_max3_f32 v0, v0, v98, v99
	v_max3_f32 v0, v0, v100, v101
	v_max3_f32 v0, v0, v102, v103
	v_max3_f32 v0, v0, v104, v105
	v_max3_f32 v0, v0, v106, v107
	v_max3_f32 v0, v0, v108, v109
	v_max3_f32 v0, v0, v110, v111
	s_nop 0
	v_max3_f32 v0, v0, v80, v81
	v_max3_f32 v0, v0, v82, v83
	v_max3_f32 v0, v0, v84, v85
	v_mbcnt_hi_u32_b32 v3, -1, v223
	v_max3_f32 v0, v0, v86, v87
	v_and_b32_e32 v4, 64, v3
	v_max3_f32 v0, v0, v88, v89
	v_xor_b32_e32 v2, 32, v3
	v_add_u32_e32 v4, 64, v4
	v_max3_f32 v0, v0, v90, v91
	v_cmp_lt_i32_e32 vcc, v2, v4
	v_max3_f32 v0, v0, v92, v93
	v_max3_f32 v0, v0, v94, v95
	v_cndmask_b32_e32 v5, v3, v2, vcc
	v_lshlrev_b32_e32 v5, 2, v5
	ds_bpermute_b32 v5, v5, v0
	s_waitcnt lgkmcnt(0)
	v_max3_f32 v5, v160, v0, v5
	v_sub_f32_e32 v0, v5, v160
	v_mul_f32_e32 v0, 0x3e38aa3b, v0
	v_cmp_lt_f32_e32 vcc, 0x41000000, v0
	s_cbranch_vccnz .Llazy_keep_6
	v_mov_b32_e32 v5, v160
.Llazy_keep_6:
	v_sub_f32_e32 v0, v160, v5
	v_mul_f32_e32 v0, 0x3e38aa3b, v0
	v_exp_f32_e32 v0, v0
	s_nop 0
	v_cmp_neq_f32_e32 vcc, 1.0, v0
	s_cbranch_vccz .LBB0_253
	v_mul_f32_e32 v112, v148, v0
	v_pk_mul_f32 v[78:79], v[0:1], v[78:79] op_sel_hi:[0,1]
	v_pk_mul_f32 v[76:77], v[0:1], v[76:77] op_sel_hi:[0,1]
	v_pk_mul_f32 v[74:75], v[0:1], v[74:75] op_sel_hi:[0,1]
	v_pk_mul_f32 v[72:73], v[0:1], v[72:73] op_sel_hi:[0,1]
	v_pk_mul_f32 v[70:71], v[0:1], v[70:71] op_sel_hi:[0,1]
	v_pk_mul_f32 v[68:69], v[0:1], v[68:69] op_sel_hi:[0,1]
	v_pk_mul_f32 v[66:67], v[0:1], v[66:67] op_sel_hi:[0,1]
	v_pk_mul_f32 v[64:65], v[0:1], v[64:65] op_sel_hi:[0,1]
	v_pk_mul_f32 v[62:63], v[0:1], v[62:63] op_sel_hi:[0,1]
	v_pk_mul_f32 v[60:61], v[0:1], v[60:61] op_sel_hi:[0,1]
	v_pk_mul_f32 v[58:59], v[0:1], v[58:59] op_sel_hi:[0,1]
	v_pk_mul_f32 v[56:57], v[0:1], v[56:57] op_sel_hi:[0,1]
	v_pk_mul_f32 v[54:55], v[0:1], v[54:55] op_sel_hi:[0,1]
	v_pk_mul_f32 v[52:53], v[0:1], v[52:53] op_sel_hi:[0,1]
	v_pk_mul_f32 v[50:51], v[0:1], v[50:51] op_sel_hi:[0,1]
	v_pk_mul_f32 v[48:49], v[0:1], v[48:49] op_sel_hi:[0,1]
	v_pk_mul_f32 v[46:47], v[0:1], v[46:47] op_sel_hi:[0,1]
	v_pk_mul_f32 v[44:45], v[0:1], v[44:45] op_sel_hi:[0,1]
	v_pk_mul_f32 v[42:43], v[0:1], v[42:43] op_sel_hi:[0,1]
	v_pk_mul_f32 v[40:41], v[0:1], v[40:41] op_sel_hi:[0,1]
	v_pk_mul_f32 v[38:39], v[0:1], v[38:39] op_sel_hi:[0,1]
	v_pk_mul_f32 v[36:37], v[0:1], v[36:37] op_sel_hi:[0,1]
	v_pk_mul_f32 v[34:35], v[0:1], v[34:35] op_sel_hi:[0,1]
	v_pk_mul_f32 v[32:33], v[0:1], v[32:33] op_sel_hi:[0,1]
	v_pk_mul_f32 v[30:31], v[0:1], v[30:31] op_sel_hi:[0,1]
	v_pk_mul_f32 v[28:29], v[0:1], v[28:29] op_sel_hi:[0,1]
	v_pk_mul_f32 v[26:27], v[0:1], v[26:27] op_sel_hi:[0,1]
	v_pk_mul_f32 v[24:25], v[0:1], v[24:25] op_sel_hi:[0,1]
	v_pk_mul_f32 v[22:23], v[0:1], v[22:23] op_sel_hi:[0,1]
	v_pk_mul_f32 v[20:21], v[0:1], v[20:21] op_sel_hi:[0,1]
	v_pk_mul_f32 v[18:19], v[0:1], v[18:19] op_sel_hi:[0,1]
	v_pk_mul_f32 v[16:17], v[0:1], v[16:17] op_sel_hi:[0,1]
	s_branch .LBB0_254

; template <int DQK, int MODE>
; DI void attn_core(const u16* __restrict__ Qg, int ldq, const u16* __restrict__ Kg, int ldk, const u16* __restrict__ Vtg,
;                   const u64* __restrict__ maskg, int q0, float scale, char* smem, int* sflags, f32x16 (&o)[4], float& l_run) {
;     ...
; #pragma unroll
;       for (int kt = 0; kt < 2; ++kt)
; #pragma unroll
;         for (int i = 0; i < 16; ++i) mx = fmaxf(mx, s[kt][i]);
;       mx = fmaxf(mx, __shfl_xor(mx, 32));
;       const float m_new = fmaxf(m_run, mx);
;       const float alpha = __builtin_amdgcn_exp2f((m_run - m_new) * sc);
;       m_run = m_new;
;       const float msc = -m_new * sc;
;       float ls = 0.f;
; #pragma unroll
;       for (int kt = 0; kt < 2; ++kt)
; #pragma unroll
;         for (int i = 0; i < 16; ++i) {
;           float pv = __builtin_amdgcn_exp2f(__builtin_fmaf(s[kt][i], sc, msc));
;           if (MODE == 1) pv = (s[kt][i] > -1e29f) ? pv : 0.f;
;           s[kt][i] = pv;
;           ls += pv;
;         }
;       if (__any(alpha != 1.0f)) {
;         l_run *= alpha;
; #pragma unroll
;         for (int t = 0; t < 4; ++t)
; #pragma unroll
;           for (int i = 0; i < 16; ++i) o[t][i] *= alpha;
;       }
.LBB0_261:
	s_or_b64 exec, exec, s[4:5]
	v_max3_f32 v0, v96, s58, v97
	v_max3_f32 v0, v0, v98, v99
	v_max3_f32 v0, v0, v100, v101
	v_max3_f32 v0, v0, v102, v103
	v_max3_f32 v0, v0, v104, v105
	v_max3_f32 v0, v0, v106, v107
	v_max3_f32 v0, v0, v108, v109
	v_max3_f32 v0, v0, v110, v111
	s_nop 0
	v_max3_f32 v0, v0, v80, v81
	v_max3_f32 v0, v0, v82, v83
	v_max3_f32 v0, v0, v84, v85
	v_max3_f32 v0, v0, v86, v87
	v_max3_f32 v0, v0, v88, v89
	v_max3_f32 v0, v0, v90, v91
	v_max3_f32 v0, v0, v92, v93
	v_max3_f32 v0, v0, v94, v95
	ds_bpermute_b32 v2, v226, v0
	s_waitcnt lgkmcnt(0)
	v_max3_f32 v2, v162, v0, v2
	v_sub_f32_e32 v0, v2, v162
	v_mul_f32_e32 v0, 0x3e38aa3b, v0
	v_cmp_lt_f32_e32 vcc, 0x41000000, v0
	s_cbranch_vccnz .Llazy_keep_7
	v_mov_b32_e32 v2, v162
.Llazy_keep_7:
	v_sub_f32_e32 v0, v162, v2
	v_mul_f32_e32 v0, 0x3e38aa3b, v0
	v_exp_f32_e32 v0, v0
	s_nop 0
	v_cmp_neq_f32_e32 vcc, 1.0, v0
	s_cbranch_vccz .LBB0_263
	v_mul_f32_e32 v143, v143, v0
	v_pk_mul_f32 v[78:79], v[0:1], v[78:79] op_sel_hi:[0,1]
	v_pk_mul_f32 v[76:77], v[0:1], v[76:77] op_sel_hi:[0,1]
	v_pk_mul_f32 v[74:75], v[0:1], v[74:75] op_sel_hi:[0,1]
	v_pk_mul_f32 v[72:73], v[0:1], v[72:73] op_sel_hi:[0,1]
	v_pk_mul_f32 v[70:71], v[0:1], v[70:71] op_sel_hi:[0,1]
	v_pk_mul_f32 v[68:69], v[0:1], v[68:69] op_sel_hi:[0,1]
	v_pk_mul_f32 v[66:67], v[0:1], v[66:67] op_sel_hi:[0,1]
	v_pk_mul_f32 v[64:65], v[0:1], v[64:65] op_sel_hi:[0,1]
	v_pk_mul_f32 v[62:63], v[0:1], v[62:63] op_sel_hi:[0,1]
	v_pk_mul_f32 v[60:61], v[0:1], v[60:61] op_sel_hi:[0,1]
	v_pk_mul_f32 v[58:59], v[0:1], v[58:59] op_sel_hi:[0,1]
	v_pk_mul_f32 v[56:57], v[0:1], v[56:57] op_sel_hi:[0,1]
	v_pk_mul_f32 v[54:55], v[0:1], v[54:55] op_sel_hi:[0,1]
	v_pk_mul_f32 v[52:53], v[0:1], v[52:53] op_sel_hi:[0,1]
	v_pk_mul_f32 v[50:51], v[0:1], v[50:51] op_sel_hi:[0,1]
	v_pk_mul_f32 v[48:49], v[0:1], v[48:49] op_sel_hi:[0,1]
	v_pk_mul_f32 v[46:47], v[0:1], v[46:47] op_sel_hi:[0,1]
	v_pk_mul_f32 v[44:45], v[0:1], v[44:45] op_sel_hi:[0,1]
	v_pk_mul_f32 v[42:43], v[0:1], v[42:43] op_sel_hi:[0,1]
	v_pk_mul_f32 v[40:41], v[0:1], v[40:41] op_sel_hi:[0,1]
	v_pk_mul_f32 v[38:39], v[0:1], v[38:39] op_sel_hi:[0,1]
	v_pk_mul_f32 v[36:37], v[0:1], v[36:37] op_sel_hi:[0,1]
	v_pk_mul_f32 v[34:35], v[0:1], v[34:35] op_sel_hi:[0,1]
	v_pk_mul_f32 v[32:33], v[0:1], v[32:33] op_sel_hi:[0,1]
	v_pk_mul_f32 v[30:31], v[0:1], v[30:31] op_sel_hi:[0,1]
	v_pk_mul_f32 v[28:29], v[0:1], v[28:29] op_sel_hi:[0,1]
	v_pk_mul_f32 v[26:27], v[0:1], v[26:27] op_sel_hi:[0,1]
	v_pk_mul_f32 v[24:25], v[0:1], v[24:25] op_sel_hi:[0,1]
	v_pk_mul_f32 v[22:23], v[0:1], v[22:23] op_sel_hi:[0,1]
	v_pk_mul_f32 v[20:21], v[0:1], v[20:21] op_sel_hi:[0,1]
	v_pk_mul_f32 v[18:19], v[0:1], v[18:19] op_sel_hi:[0,1]
	v_pk_mul_f32 v[16:17], v[0:1], v[16:17] op_sel_hi:[0,1]

; template <int DQK, int MODE>
; DI void attn_core(const u16* __restrict__ Qg, int ldq, const u16* __restrict__ Kg, int ldk, const u16* __restrict__ Vtg,
;                   const u64* __restrict__ maskg, int q0, float scale, char* smem, int* sflags, f32x16 (&o)[4], float& l_run) {
;     ...
; #pragma unroll
;       for (int kt = 0; kt < 2; ++kt)
; #pragma unroll
;         for (int i = 0; i < 16; ++i) mx = fmaxf(mx, s[kt][i]);
;       mx = fmaxf(mx, __shfl_xor(mx, 32));
;       const float m_new = fmaxf(m_run, mx);
;       const float alpha = __builtin_amdgcn_exp2f((m_run - m_new) * sc);
;       m_run = m_new;
;       const float msc = -m_new * sc;
;       float ls = 0.f;
; #pragma unroll
;       for (int kt = 0; kt < 2; ++kt)
; #pragma unroll
;         for (int i = 0; i < 16; ++i) {
;           float pv = __builtin_amdgcn_exp2f(__builtin_fmaf(s[kt][i], sc, msc));
;           if (MODE == 1) pv = (s[kt][i] > -1e29f) ? pv : 0.f;
;           s[kt][i] = pv;
;           ls += pv;
;         }
;       if (__any(alpha != 1.0f)) {
;         l_run *= alpha;
; #pragma unroll
;         for (int t = 0; t < 4; ++t)
; #pragma unroll
;           for (int i = 0; i < 16; ++i) o[t][i] *= alpha;
;       }
.LBB0_269:
	s_or_b64 exec, exec, s[2:3]
	v_max3_f32 v0, v96, s58, v97
	v_max3_f32 v0, v0, v98, v99
	v_max3_f32 v0, v0, v100, v101
	v_max3_f32 v0, v0, v102, v103
	v_max3_f32 v0, v0, v104, v105
	v_max3_f32 v0, v0, v106, v107
	v_max3_f32 v0, v0, v108, v109
	v_max3_f32 v0, v0, v110, v111
	s_nop 0
	v_max3_f32 v0, v0, v80, v81
	v_max3_f32 v0, v0, v82, v83
	v_max3_f32 v0, v0, v84, v85
	v_max3_f32 v0, v0, v86, v87
	v_max3_f32 v0, v0, v88, v89
	v_max3_f32 v0, v0, v90, v91
	v_max3_f32 v0, v0, v92, v93
	v_max3_f32 v0, v0, v94, v95
	ds_bpermute_b32 v2, v226, v0
	s_waitcnt lgkmcnt(0)
	v_max3_f32 v2, v162, v0, v2
	v_sub_f32_e32 v0, v2, v162
	v_mul_f32_e32 v0, 0x3e38aa3b, v0
	v_cmp_lt_f32_e32 vcc, 0x41000000, v0
	s_cbranch_vccnz .Llazy_keep_8
	v_mov_b32_e32 v2, v162
.Llazy_keep_8:
	v_sub_f32_e32 v0, v162, v2
	v_mul_f32_e32 v0, 0x3e38aa3b, v0
	v_exp_f32_e32 v0, v0
	s_nop 0
	v_cmp_neq_f32_e32 vcc, 1.0, v0
	s_cbranch_vccz .LBB0_200
	v_mul_f32_e32 v143, v143, v0
	v_pk_mul_f32 v[78:79], v[0:1], v[78:79] op_sel_hi:[0,1]
	v_pk_mul_f32 v[76:77], v[0:1], v[76:77] op_sel_hi:[0,1]
	v_pk_mul_f32 v[74:75], v[0:1], v[74:75] op_sel_hi:[0,1]
	v_pk_mul_f32 v[72:73], v[0:1], v[72:73] op_sel_hi:[0,1]
	v_pk_mul_f32 v[70:71], v[0:1], v[70:71] op_sel_hi:[0,1]
	v_pk_mul_f32 v[68:69], v[0:1], v[68:69] op_sel_hi:[0,1]
	v_pk_mul_f32 v[66:67], v[0:1], v[66:67] op_sel_hi:[0,1]
	v_pk_mul_f32 v[64:65], v[0:1], v[64:65] op_sel_hi:[0,1]
	v_pk_mul_f32 v[62:63], v[0:1], v[62:63] op_sel_hi:[0,1]
	v_pk_mul_f32 v[60:61], v[0:1], v[60:61] op_sel_hi:[0,1]
	v_pk_mul_f32 v[58:59], v[0:1], v[58:59] op_sel_hi:[0,1]
	v_pk_mul_f32 v[56:57], v[0:1], v[56:57] op_sel_hi:[0,1]
	v_pk_mul_f32 v[54:55], v[0:1], v[54:55] op_sel_hi:[0,1]
	v_pk_mul_f32 v[52:53], v[0:1], v[52:53] op_sel_hi:[0,1]
	v_pk_mul_f32 v[50:51], v[0:1], v[50:51] op_sel_hi:[0,1]
	v_pk_mul_f32 v[48:49], v[0:1], v[48:49] op_sel_hi:[0,1]
	v_pk_mul_f32 v[46:47], v[0:1], v[46:47] op_sel_hi:[0,1]
	v_pk_mul_f32 v[44:45], v[0:1], v[44:45] op_sel_hi:[0,1]
	v_pk_mul_f32 v[42:43], v[0:1], v[42:43] op_sel_hi:[0,1]
	v_pk_mul_f32 v[40:41], v[0:1], v[40:41] op_sel_hi:[0,1]
	v_pk_mul_f32 v[38:39], v[0:1], v[38:39] op_sel_hi:[0,1]
	v_pk_mul_f32 v[36:37], v[0:1], v[36:37] op_sel_hi:[0,1]
	v_pk_mul_f32 v[34:35], v[0:1], v[34:35] op_sel_hi:[0,1]
	v_pk_mul_f32 v[32:33], v[0:1], v[32:33] op_sel_hi:[0,1]
	v_pk_mul_f32 v[30:31], v[0:1], v[30:31] op_sel_hi:[0,1]
	v_pk_mul_f32 v[28:29], v[0:1], v[28:29] op_sel_hi:[0,1]
	v_pk_mul_f32 v[26:27], v[0:1], v[26:27] op_sel_hi:[0,1]
	v_pk_mul_f32 v[24:25], v[0:1], v[24:25] op_sel_hi:[0,1]
	v_pk_mul_f32 v[22:23], v[0:1], v[22:23] op_sel_hi:[0,1]
	v_pk_mul_f32 v[20:21], v[0:1], v[20:21] op_sel_hi:[0,1]
	v_pk_mul_f32 v[18:19], v[0:1], v[18:19] op_sel_hi:[0,1]
	v_pk_mul_f32 v[16:17], v[0:1], v[16:17] op_sel_hi:[0,1]
	s_branch .LBB0_200
